# weight-conversion split: 12072 items in the prologue
# baseline (speedup 1.0000x reference)
; #define LAS __attribute__((address_space(3)))
;     __device__ __forceinline__ bf16* Win_t() const { return (bf16*)(ws + WS_WIN); }
;     __device__ __forceinline__ bf16* Wout_t() const { return (bf16*)(ws + WS_WOUT); }
;     __device__ __forceinline__ bf16* Wgu_t() const { return (bf16*)((unsigned char*)out + OUT_WGU); }
; __device__ __forceinline__ P0Item p0_decode(Frame& F, int it, int n4) {
;     constexpr int I_IN = (D / 64) * (NP1 / 64), I_OUT = (D / 64) * (D / 64), I_GU = (D / 64) * (2 * FF / 64);
;     P0Item q; int r = it;
;     if (r < I_IN) { const int nblk = NP1 / 64, kb = r / nblk, nb = r % nblk, n = nb * 64 + n4;
;         const int sc = n < SRC_GLR ? n : n + GRANK;
;         q.srcp = F.w_in + sc; q.ldw = DIN; q.kscale = F.norm1_w; q.K = D; q.WT = F.Win_t(); q.n0 = nb * 64; q.k0 = kb * 64; return q; }
;     r -= I_IN;
;     if (r < I_OUT) { const int nblk = D / 64, kb = r / nblk, nb = r % nblk;
;         q.srcp = F.w_out + nb * 64 + n4; q.ldw = D; q.kscale = nullptr; q.K = D; q.WT = F.Wout_t(); q.n0 = nb * 64; q.k0 = kb * 64; return q; }
;     r -= I_OUT;
;     if (r < I_GU) { const int nblk = 2 * FF / 64, kb = r / nblk, nb = r % nblk, n0 = nb * 64, pn = n0 >> 8, wc = (n0 >> 6) & 3, bj = n4 >> 5, hl = 32 * wc + (n4 & 31);
;         q.srcp = (bj ? F.w_up : F.w_gate) + pn * 128 + hl; q.ldw = FF; q.kscale = F.norm2_w; q.K = D; q.WT = F.Wgu_t(); q.n0 = n0; q.k0 = kb * 64; return q; }
; template <bool NT> __device__ __forceinline__ void p0_items(Frame& F, int it0, int it1, int gw, int nw) {
;     LAS unsigned char* scr = F.lds + F.wave * 16384;
;     const int n4 = (F.lane & 15) * 4, kr = F.lane >> 4;
;     f32x4 va[16], vb[16]; P0Item A, B; int it = it0 + gw;
;     if (it < it1) { A = p0_decode(F, it, n4); p0_load(A, kr, va); }
.LBB0_16:
	s_add_u32 s4, s54, 0x4000000
	s_addc_u32 s5, s55, 0
	v_lshlrev_b32_e32 v2, 2, v183
	s_add_u32 s6, s56, 0xa00000
	v_and_b32_e32 v141, 60, v2
	s_addc_u32 s7, s57, 0
	s_add_u32 s18, s56, 0x2800000
	v_and_b32_e32 v142, 28, v2
	v_mov_b32_e32 v2, s93
	v_mov_b32_e32 v3, s91
	v_cmp_gt_u32_e32 vcc, 32, v141
	v_lshrrev_b32_e32 v1, 4, v183
	s_addc_u32 s19, s57, 0
	v_cndmask_b32_e32 v135, v2, v3, vcc
	v_mov_b32_e32 v2, s92
	v_mov_b32_e32 v3, s90
	s_cmpk_gt_i32 s16, 0x2f27
	v_cndmask_b32_e32 v134, v2, v3, vcc
	v_or_b32_e32 v143, 4, v1
	v_or_b32_e32 v145, 8, v1
	v_or_b32_e32 v146, 12, v1
	v_or_b32_e32 v147, 16, v1
	v_or_b32_e32 v148, 20, v1
	v_or_b32_e32 v149, 24, v1
	v_or_b32_e32 v150, 28, v1
	v_or_b32_e32 v151, 32, v1
	v_or_b32_e32 v152, 36, v1
	v_or_b32_e32 v153, 40, v1
	v_or_b32_e32 v154, 44, v1
	v_or_b32_e32 v155, 48, v1
	v_or_b32_e32 v156, 52, v1
	v_or_b32_e32 v157, 56, v1
	v_or_b32_e32 v158, 60, v1
	s_cbranch_scc1 .LBB0_19
	s_mul_hi_i32 s1, s16, 0x51eb851f
	s_lshr_b32 s8, s1, 31
	s_ashr_i32 s1, s1, 6
	s_add_i32 s1, s1, s8
	s_mul_i32 s8, s1, 0xc8
	s_sub_i32 s8, s16, s8
	s_lshl_b32 s17, s8, 6
	v_or_b32_e32 v2, s17, v141
	s_movk_i32 s8, 0x1a00
	s_cmpk_lt_i32 s16, 0x1900
	v_cmp_gt_i32_e32 vcc, s8, v2
	s_cbranch_scc1 .LBB0_20
	s_cmpk_lt_u32 s16, 0x1d00
	s_cselect_b64 vcc, -1, 0
	s_add_i32 s1, s16, 0xe300
	s_and_b32 s8, s1, 0xffff
	s_mul_i32 s8, s8, 0xba2f
	s_lshr_b32 s8, s8, 23
	s_mul_i32 s9, s8, 0xb0
	s_sub_i32 s1, s1, s9
	s_and_b32 s1, s1, 0xffff
	s_lshl_b32 s10, s1, 5
	s_and_b32 s10, s10, 0x60
	s_lshl_b32 s9, s1, 6
	v_or_b32_e32 v4, s10, v142
	s_lshl_b32 s1, s1, 7
	s_and_b32 s10, s0, 0x7c0
	s_and_b32 s20, s1, 0x7e00
	s_mov_b32 s21, 0
	s_lshl_b32 s8, s8, 6
	s_lshl_b32 s0, s10, 2
	v_lshl_add_u64 v[2:3], v[134:135], 0, s[20:21]
	v_lshlrev_b32_e32 v4, 2, v4
	v_mov_b32_e32 v5, 0
	s_add_u32 s0, s50, s0
	v_lshl_add_u64 v[2:3], v[2:3], 0, v[4:5]
	s_addc_u32 s1, s51, 0
	v_lshlrev_b32_e32 v4, 2, v141
	v_lshl_add_u64 v[4:5], s[0:1], 0, v[4:5]
	s_lshl_b32 s0, s16, 1
	s_and_b32 s0, s0, 0x3fc0
	s_add_i32 s11, s0, 0xffffce00
	s_and_b64 s[0:1], vcc, exec
	s_movk_i32 s0, 0x800
	v_cndmask_b32_e32 v27, v3, v5, vcc
	v_cndmask_b32_e32 v26, v2, v4, vcc
	s_cselect_b32 s23, 0, s89
	s_cselect_b32 s22, 0, s88
	s_cselect_b32 s25, s7, s5
	s_cselect_b32 s24, s6, s4
	s_cselect_b32 s20, s0, 0x1600
	s_cselect_b32 s17, s10, s9
	s_cselect_b32 s63, s11, s8
	s_branch .LBB0_21

;     __device__ __forceinline__ bf16* Win_t() const { return (bf16*)(ws + WS_WIN); }
;     __device__ __forceinline__ bf16* Wout_t() const { return (bf16*)(ws + WS_WOUT); }
;     __device__ __forceinline__ bf16* Wgu_t() const { return (bf16*)((unsigned char*)out + OUT_WGU); }
; __device__ __forceinline__ P0Item p0_decode(Frame& F, int it, int n4) {
;     ...
;     if (r < I_IN) { const int nblk = NP1 / 64, kb = r / nblk, nb = r % nblk, n = nb * 64 + n4;
;         const int sc = n < SRC_GLR ? n : n + GRANK;
;         q.srcp = F.w_in + sc; q.ldw = DIN; q.kscale = F.norm1_w; q.K = D; q.WT = F.Win_t(); q.n0 = nb * 64; q.k0 = kb * 64; return q; }
;     r -= I_IN;
;     if (r < I_OUT) { const int nblk = D / 64, kb = r / nblk, nb = r % nblk;
;         q.srcp = F.w_out + nb * 64 + n4; q.ldw = D; q.kscale = nullptr; q.K = D; q.WT = F.Wout_t(); q.n0 = nb * 64; q.k0 = kb * 64; return q; }
;     r -= I_OUT;
;     if (r < I_GU) { const int nblk = 2 * FF / 64, kb = r / nblk, nb = r % nblk, n0 = nb * 64, pn = n0 >> 8, wc = (n0 >> 6) & 3, bj = n4 >> 5, hl = 32 * wc + (n4 & 31);
;         q.srcp = (bj ? F.w_up : F.w_gate) + pn * 128 + hl; q.ldw = FF; q.kscale = F.norm2_w; q.K = D; q.WT = F.Wgu_t(); q.n0 = n0; q.k0 = kb * 64; return q; }
; template <bool NT> __device__ __forceinline__ void p0_items(Frame& F, int it0, int it1, int gw, int nw) {
;     ...
;     while (it < it1) {
;         int itn = it + nw;
;         if (itn < it1) { B = p0_decode(F, itn, n4); p0_load(B, kr, vb); }
;         p0_finish<NT>(A, va, scr, F.lane);
;         it = itn; if (it >= it1) break;
;         itn = it + nw;
;         if (itn < it1) { A = p0_decode(F, itn, n4); p0_load(A, kr, va); }
.LBB0_57:
	s_cmpk_gt_i32 s65, 0x2f27
	s_mov_b64 s[34:35], -1
	s_cbranch_scc1 .LBB0_56
	s_add_i32 s65, s65, s20
	s_cmpk_lt_i32 s65, 0x2f28
	s_cselect_b64 s[68:69], -1, 0
	s_cmpk_gt_i32 s65, 0x2f27
	s_cselect_b64 s[34:35], -1, 0
	s_and_b64 vcc, exec, s[34:35]
	s_cbranch_vccnz .LBB0_100
	s_cmpk_gt_i32 s65, 0x18ff
	s_cbranch_scc0 .LBB0_62
	s_cmpk_gt_u32 s65, 0x1cff
	s_cbranch_scc0 .LBB0_63
	s_add_i32 s0, s65, 0xe300
	s_and_b32 s1, s0, 0xffff
	s_mul_i32 s1, s1, 0xba2f
	s_lshr_b32 s1, s1, 23
	s_mul_i32 s8, s1, 0xb0
	s_sub_i32 s0, s0, s8
	s_and_b32 s0, s0, 0xffff
	s_lshl_b32 s8, s0, 5
	s_lshl_b32 s67, s0, 6
	s_and_b32 s8, s8, 0x60
	s_lshl_b32 s0, s0, 7
	v_or_b32_e32 v27, s8, v142
	s_and_b32 s26, s0, 0x7e00
	v_lshl_add_u64 v[28:29], v[134:135], 0, s[26:27]
	v_lshlrev_b32_e32 v46, 2, v27
	v_mov_b32_e32 v47, v26
	v_lshl_add_u64 v[138:139], v[28:29], 0, v[46:47]
	s_lshl_b32 s74, s1, 6
	s_mov_b64 s[28:29], s[88:89]
	s_mov_b64 s[70:71], 0x1600
	s_mov_b64 s[30:31], s[4:5]
	s_cbranch_execz .LBB0_64
	s_branch .LBB0_65

; #define GAS __attribute__((address_space(1)))
; #define LAS __attribute__((address_space(3)))
; __device__ __forceinline__ s16x4_t tr_read(LAS const unsigned char* p) { return __builtin_bit_cast(s16x4_t, __builtin_amdgcn_ds_read_tr16_b64_v4i16((LAS s16x4_t*)p)); }
; __device__ __forceinline__ bf16x8_t cat8(s16x4_t lo, s16x4_t hi) { return __builtin_shufflevector(lo, hi, 0, 1, 2, 3, 4, 5, 6, 7); }
; template <bool NT> __device__ __forceinline__ void p0_finish(const P0Item& q, f32x4 (&v)[16], LAS unsigned char* scr, int lane) {
;     ...
;         for (int i = 0; i < 16; ++i) v[i] = v[i] * q.kscale[q.k0 + 4 * i + kr];
;     }
; #pragma unroll
;     for (int i = 0; i < 16; ++i) { v2u w; w.x = cvtpk(v[i][0], v[i][1]); w.y = cvtpk(v[i][2], v[i][3]); *(LAS v2u*)(scr + (4 * i + kr) * RS + n4 * 2) = w; }
;     const int G = lane >> 4, i16 = lane & 15, qq = i16 >> 2, p = i16 & 3;
; #pragma unroll
;     for (int ng = 0; ng < 4; ++ng)
; #pragma unroll
;         for (int u = 0; u < 2; ++u) { const LAS unsigned char* rp = scr + (8 * (G + 4 * u) + qq) * RS + (16 * ng + 4 * p) * 2;
;             const bf16x8_t t = cat8(tr_read(rp), tr_read(rp + 4 * RS));
;             *(GAS bf16x8_t*)(q.WT + pg8::blk_off_b(q.n0 + 16 * ng + i16, q.k0 + 8 * (G + 4 * u), q.K)) = t; }
.LBB0_102:
	s_waitcnt vmcnt(0)
	v_cvt_pk_bf16_f32 v28, v2, v3
	v_cvt_pk_bf16_f32 v29, v4, v5
	v_cvt_pk_bf16_f32 v138, v6, v7
	v_cvt_pk_bf16_f32 v139, v8, v9
	ds_write2_b64 v165, v[28:29], v[138:139] offset1:72
	v_cvt_pk_bf16_f32 v28, v10, v11
	v_cvt_pk_bf16_f32 v29, v12, v13
	v_cvt_pk_bf16_f32 v138, v14, v15
	v_cvt_pk_bf16_f32 v139, v16, v17
	ds_write2_b64 v165, v[28:29], v[138:139] offset0:144 offset1:216
	v_cvt_pk_bf16_f32 v28, v18, v19
	v_cvt_pk_bf16_f32 v29, v20, v21
	v_cvt_pk_bf16_f32 v138, v22, v23
	v_cvt_pk_bf16_f32 v139, v24, v25
	v_add_u32_e32 v168, 0x800, v165
	ds_write2_b64 v168, v[28:29], v[138:139] offset0:32 offset1:104
	v_cvt_pk_bf16_f32 v28, v30, v31
	v_cvt_pk_bf16_f32 v29, v32, v33
	v_cvt_pk_bf16_f32 v138, v34, v35
	v_cvt_pk_bf16_f32 v139, v36, v37
	ds_write2_b64 v168, v[28:29], v[138:139] offset0:176 offset1:248
	v_cvt_pk_bf16_f32 v28, v38, v39
	v_cvt_pk_bf16_f32 v29, v40, v41
	v_cvt_pk_bf16_f32 v138, v42, v43
	v_cvt_pk_bf16_f32 v139, v44, v45
	v_add_u32_e32 v169, 0x1000, v165
	ds_write2_b64 v169, v[28:29], v[138:139] offset0:64 offset1:136
	v_cvt_pk_bf16_f32 v28, v50, v51
	v_cvt_pk_bf16_f32 v29, v52, v53
	v_cvt_pk_bf16_f32 v138, v58, v59
	v_cvt_pk_bf16_f32 v139, v60, v61
	v_add_u32_e32 v170, 0x1400, v165
	ds_write2_b64 v170, v[28:29], v[138:139] offset0:80 offset1:152
	v_cvt_pk_bf16_f32 v28, v74, v75
	v_cvt_pk_bf16_f32 v29, v76, v77
	v_cvt_pk_bf16_f32 v138, v82, v83
	v_cvt_pk_bf16_f32 v139, v84, v85
	v_add_u32_e32 v171, 0x1800, v165
	ds_write2_b64 v171, v[28:29], v[138:139] offset0:96 offset1:168
	v_cvt_pk_bf16_f32 v28, v94, v95
	v_cvt_pk_bf16_f32 v29, v96, v97
	v_cvt_pk_bf16_f32 v138, v102, v103
	v_cvt_pk_bf16_f32 v139, v104, v105
	v_add_u32_e32 v172, 0x1c00, v165
	v_add_u32_e32 v27, s17, v140
	ds_write2_b64 v172, v[28:29], v[138:139] offset0:112 offset1:184
	v_lshlrev_b32_e32 v28, 2, v27
	v_and_b32_e32 v28, 16, v28
	v_lshrrev_b32_e32 v29, 1, v27
	v_add_u32_e32 v138, s63, v160
	v_and_or_b32 v173, v29, s21, v28
	v_ashrrev_i32_e32 v28, 3, v27
	v_and_b32_e32 v139, 3, v27
	v_and_b32_e32 v182, 0xffffffe0, v28
	v_ashrrev_i32_e32 v204, 6, v138
	v_and_or_b32 v139, v29, 12, v139
	v_add_u32_e32 v28, v182, v204
	ds_read_b64_tr_b16 v[176:177], v166 offset:576
	v_ashrrev_i32_e32 v29, 31, v28
	v_lshlrev_b32_e32 v192, 5, v139
	v_and_b32_e32 v206, 31, v138
	v_and_b32_e32 v193, 16, v27
	v_lshrrev_b32_e32 v173, 3, v173
	v_bfe_u32 v205, v138, 5, 1
	v_bitop3_b32 v175, v192, v193, v206 bitop3:0x36
	v_lshlrev_b64 v[28:29], 15, v[28:29]
	v_lshlrev_b32_e32 v27, 9, v27
	v_or_b32_e32 v174, v173, v205
	v_lshl_add_u64 v[28:29], s[24:25], 0, v[28:29]
	v_and_b32_e32 v138, 0x4000, v27
	v_mov_b32_e32 v139, v26
	v_lshlrev_b32_e32 v27, 1, v175
	v_lshl_add_u64 v[28:29], v[28:29], 0, v[138:139]
	v_lshl_or_b32 v174, v174, 10, v27
	v_mov_b32_e32 v175, v26
	v_add_u32_e32 v27, s63, v161
	v_lshl_add_u64 v[28:29], v[28:29], 0, v[174:175]
	v_ashrrev_i32_e32 v207, 6, v27
	ds_read_b64_tr_b16 v[174:175], v166
	ds_read_b64_tr_b16 v[178:179], v166 offset:32
	ds_read_b64_tr_b16 v[184:185], v166 offset:64
	ds_read_b64_tr_b16 v[188:189], v166 offset:96
	ds_read_b64_tr_b16 v[180:181], v166 offset:608
	ds_read_b64_tr_b16 v[186:187], v166 offset:640
	ds_read_b64_tr_b16 v[190:191], v166 offset:672
	s_waitcnt lgkmcnt(6)
	global_store_dwordx4 v[28:29], v[174:177], off
	v_add_u32_e32 v28, v182, v207
	v_ashrrev_i32_e32 v29, 31, v28
	ds_read_b64_tr_b16 v[176:177], v167 offset:576
	v_bfe_u32 v182, v27, 5, 1
	v_and_b32_e32 v27, 31, v27
	v_lshlrev_b64 v[28:29], 15, v[28:29]
	v_bitop3_b32 v174, v192, v193, v27 bitop3:0x36
	v_lshl_add_u64 v[28:29], s[24:25], 0, v[28:29]
	v_or_b32_e32 v173, v173, v182
	v_lshl_add_u64 v[28:29], v[28:29], 0, v[138:139]
	v_lshlrev_b32_e32 v138, 1, v174
	v_lshl_or_b32 v138, v173, 10, v138
	v_lshl_add_u64 v[28:29], v[28:29], 0, v[138:139]
	v_add_u32_e32 v138, s17, v162
	ds_read_b64_tr_b16 v[174:175], v167
	ds_read_b64_tr_b16 v[192:193], v167 offset:32
	ds_read_b64_tr_b16 v[196:197], v167 offset:64
	ds_read_b64_tr_b16 v[200:201], v167 offset:96
	ds_read_b64_tr_b16 v[194:195], v167 offset:608
	ds_read_b64_tr_b16 v[198:199], v167 offset:640
	ds_read_b64_tr_b16 v[202:203], v167 offset:672
	s_waitcnt lgkmcnt(6)
; #define GAS __attribute__((address_space(1)))
; #define LAS __attribute__((address_space(3)))
; #define LDS_WAIT() asm volatile("s_waitcnt lgkmcnt(0)" ::: "memory")
; __device__ __forceinline__ s16x4_t tr_read(LAS const unsigned char* p) { return __builtin_bit_cast(s16x4_t, __builtin_amdgcn_ds_read_tr16_b64_v4i16((LAS s16x4_t*)p)); }
; __device__ __forceinline__ bf16x8_t cat8(s16x4_t lo, s16x4_t hi) { return __builtin_shufflevector(lo, hi, 0, 1, 2, 3, 4, 5, 6, 7); }
; template <bool NT> __device__ __forceinline__ void p0_finish(const P0Item& q, f32x4 (&v)[16], LAS unsigned char* scr, int lane) {
;     ...
;         for (int u = 0; u < 2; ++u) { const LAS unsigned char* rp = scr + (8 * (G + 4 * u) + qq) * RS + (16 * ng + 4 * p) * 2;
;             const bf16x8_t t = cat8(tr_read(rp), tr_read(rp + 4 * RS));
;             *(GAS bf16x8_t*)(q.WT + pg8::blk_off_b(q.n0 + 16 * ng + i16, q.k0 + 8 * (G + 4 * u), q.K)) = t; }
;     LDS_WAIT(); asm volatile("" ::: "memory");
; }
; template <bool NT> __device__ __forceinline__ void p0_items(Frame& F, int it0, int it1, int gw, int nw) {
;     LAS unsigned char* scr = F.lds + F.wave * 16384;
;     const int n4 = (F.lane & 15) * 4, kr = F.lane >> 4;
;     f32x4 va[16], vb[16]; P0Item A, B; int it = it0 + gw;
;     if (it < it1) { A = p0_decode(F, it, n4); p0_load(A, kr, va); }
;     while (it < it1) {
;         int itn = it + nw;
;         if (itn < it1) { B = p0_decode(F, itn, n4); p0_load(B, kr, vb); }
;         p0_finish<NT>(A, va, scr, F.lane);
;         it = itn; if (it >= it1) break;
;         itn = it + nw;
;         if (itn < it1) { A = p0_decode(F, itn, n4); p0_load(A, kr, va); }
;         p0_finish<NT>(B, vb, scr, F.lane);
;         it = itn;
	global_store_dwordx4 v[28:29], v[174:177], off
	v_lshlrev_b32_e32 v28, 2, v138
	v_and_b32_e32 v28, 16, v28
	v_lshrrev_b32_e32 v29, 1, v138
	v_and_or_b32 v173, v29, s21, v28
	v_ashrrev_i32_e32 v28, 3, v138
	v_and_b32_e32 v139, 3, v138
	v_and_b32_e32 v176, 0xffffffe0, v28
	v_and_or_b32 v139, v29, 12, v139
	v_add_u32_e32 v28, v176, v204
	v_ashrrev_i32_e32 v29, 31, v28
	v_lshlrev_b32_e32 v177, 5, v139
	v_and_b32_e32 v208, 16, v138
	v_lshrrev_b32_e32 v173, 3, v173
	v_bitop3_b32 v175, v177, v208, v206 bitop3:0x36
	v_lshlrev_b64 v[28:29], 15, v[28:29]
	v_lshlrev_b32_e32 v138, 9, v138
	v_or_b32_e32 v174, v173, v205
	v_lshl_add_u64 v[28:29], s[24:25], 0, v[28:29]
	v_and_b32_e32 v138, 0x4000, v138
	v_mov_b32_e32 v139, v26
	v_lshlrev_b32_e32 v175, 1, v175
	v_lshl_add_u64 v[28:29], v[28:29], 0, v[138:139]
	v_lshl_or_b32 v174, v174, 10, v175
	v_mov_b32_e32 v175, v26
	v_lshl_add_u64 v[28:29], v[28:29], 0, v[174:175]
	global_store_dwordx4 v[28:29], v[178:181], off
	v_add_u32_e32 v28, v176, v207
	v_ashrrev_i32_e32 v29, 31, v28
	v_lshlrev_b64 v[28:29], 15, v[28:29]
	v_bitop3_b32 v174, v177, v208, v27 bitop3:0x36
	v_lshl_add_u64 v[28:29], s[24:25], 0, v[28:29]
	v_or_b32_e32 v173, v173, v182
	v_lshl_add_u64 v[28:29], v[28:29], 0, v[138:139]
	v_lshlrev_b32_e32 v138, 1, v174
	v_lshl_or_b32 v138, v173, 10, v138
	v_lshl_add_u64 v[28:29], v[28:29], 0, v[138:139]
	v_add_u32_e32 v138, s17, v163
	s_waitcnt lgkmcnt(2)
	global_store_dwordx4 v[28:29], v[192:195], off
	v_lshlrev_b32_e32 v28, 2, v138
	v_and_b32_e32 v28, 16, v28
	v_lshrrev_b32_e32 v29, 1, v138
	v_and_or_b32 v173, v29, s21, v28
	v_ashrrev_i32_e32 v28, 3, v138
	v_and_b32_e32 v139, 3, v138
	v_and_b32_e32 v176, 0xffffffe0, v28
	v_and_or_b32 v139, v29, 12, v139
	v_add_u32_e32 v28, v176, v204
	v_ashrrev_i32_e32 v29, 31, v28
	v_lshlrev_b32_e32 v177, 5, v139
	v_and_b32_e32 v178, 16, v138
	v_lshrrev_b32_e32 v173, 3, v173
	v_bitop3_b32 v175, v177, v178, v206 bitop3:0x36
	v_lshlrev_b64 v[28:29], 15, v[28:29]
	v_lshlrev_b32_e32 v138, 9, v138
	v_or_b32_e32 v174, v173, v205
	v_lshl_add_u64 v[28:29], s[24:25], 0, v[28:29]
	v_and_b32_e32 v138, 0x4000, v138
	v_mov_b32_e32 v139, v26
	v_lshlrev_b32_e32 v175, 1, v175
	v_lshl_add_u64 v[28:29], v[28:29], 0, v[138:139]
	v_lshl_or_b32 v174, v174, 10, v175
	v_mov_b32_e32 v175, v26
	v_lshl_add_u64 v[28:29], v[28:29], 0, v[174:175]
	global_store_dwordx4 v[28:29], v[184:187], off
	v_add_u32_e32 v28, v176, v207
	v_ashrrev_i32_e32 v29, 31, v28
	v_lshlrev_b64 v[28:29], 15, v[28:29]
	v_bitop3_b32 v174, v177, v178, v27 bitop3:0x36
	v_lshl_add_u64 v[28:29], s[24:25], 0, v[28:29]
	v_or_b32_e32 v173, v173, v182
	v_lshl_add_u64 v[28:29], v[28:29], 0, v[138:139]
	v_lshlrev_b32_e32 v138, 1, v174
	v_lshl_or_b32 v138, v173, 10, v138
	v_lshl_add_u64 v[28:29], v[28:29], 0, v[138:139]
	v_add_u32_e32 v138, s17, v164
	s_waitcnt lgkmcnt(1)
	global_store_dwordx4 v[28:29], v[196:199], off
	v_lshlrev_b32_e32 v28, 2, v138
	v_and_b32_e32 v28, 16, v28
	v_lshrrev_b32_e32 v29, 1, v138
	v_and_or_b32 v173, v29, s21, v28
	v_ashrrev_i32_e32 v28, 3, v138
	v_and_b32_e32 v139, 3, v138
	v_and_b32_e32 v176, 0xffffffe0, v28
	v_and_or_b32 v139, v29, 12, v139
	v_add_u32_e32 v28, v176, v204
	v_ashrrev_i32_e32 v29, 31, v28
	v_lshlrev_b32_e32 v177, 5, v139
	v_and_b32_e32 v178, 16, v138
	v_lshrrev_b32_e32 v173, 3, v173
	v_bitop3_b32 v175, v177, v178, v206 bitop3:0x36
	v_lshlrev_b64 v[28:29], 15, v[28:29]
	v_lshlrev_b32_e32 v138, 9, v138
	v_or_b32_e32 v174, v173, v205
	v_lshl_add_u64 v[28:29], s[24:25], 0, v[28:29]
	v_and_b32_e32 v138, 0x4000, v138
	v_mov_b32_e32 v139, v26
	v_lshlrev_b32_e32 v175, 1, v175
	v_lshl_add_u64 v[28:29], v[28:29], 0, v[138:139]
	v_lshl_or_b32 v174, v174, 10, v175
	v_mov_b32_e32 v175, v26
	v_lshl_add_u64 v[28:29], v[28:29], 0, v[174:175]
	global_store_dwordx4 v[28:29], v[188:191], off
	v_add_u32_e32 v28, v176, v207
	v_ashrrev_i32_e32 v29, 31, v28
	v_bitop3_b32 v27, v177, v178, v27 bitop3:0x36
	v_lshlrev_b64 v[28:29], 15, v[28:29]
	v_or_b32_e32 v173, v173, v182
	v_lshl_add_u64 v[28:29], s[24:25], 0, v[28:29]
	v_lshlrev_b32_e32 v27, 1, v27
	v_lshl_add_u64 v[28:29], v[28:29], 0, v[138:139]
	v_lshl_or_b32 v138, v173, 10, v27
	v_lshl_add_u64 v[28:29], v[28:29], 0, v[138:139]
	s_waitcnt lgkmcnt(0)
	global_store_dwordx4 v[28:29], v[200:203], off
	s_waitcnt lgkmcnt(0)
	s_andn2_b64 vcc, exec, s[68:69]
	s_cbranch_vccnz .LBB0_56
	s_add_i32 s65, s65, s20
	s_cmpk_gt_i32 s65, 0x2f27
	s_cbranch_scc1 .LBB0_145
	s_cmpk_gt_i32 s65, 0x18ff
	s_cbranch_scc0 .LBB0_107
	s_cmpk_gt_u32 s65, 0x1cff
	s_cbranch_scc0 .LBB0_108
	s_add_i32 s0, s65, 0xe300
	s_and_b32 s1, s0, 0xffff
	s_mul_i32 s1, s1, 0xba2f
	s_lshr_b32 s1, s1, 23
	s_mul_i32 s8, s1, 0xb0
	s_sub_i32 s0, s0, s8
	s_and_b32 s0, s0, 0xffff
	s_lshl_b32 s8, s0, 5
	s_lshl_b32 s17, s0, 6
	s_and_b32 s8, s8, 0x60
	s_lshl_b32 s0, s0, 7
	v_or_b32_e32 v4, s8, v142
	s_and_b32 s26, s0, 0x7e00
	v_lshl_add_u64 v[2:3], v[134:135], 0, s[26:27]
	v_lshlrev_b32_e32 v4, 2, v4
	v_mov_b32_e32 v5, v26
	v_lshl_add_u64 v[138:139], v[2:3], 0, v[4:5]
	s_lshl_b32 s63, s1, 6
	s_mov_b64 s[22:23], s[88:89]
	s_mov_b64 s[68:69], 0x1600
	s_mov_b64 s[24:25], s[4:5]
	s_cbranch_execz .LBB0_109
	s_branch .LBB0_110

;     __device__ __forceinline__ bf16* Win_t() const { return (bf16*)(ws + WS_WIN); }
;     __device__ __forceinline__ bf16* Wout_t() const { return (bf16*)(ws + WS_WOUT); }
;     __device__ __forceinline__ bf16* Wdown_t() const { return (bf16*)(ws + WS_WDOWN); }
;     __device__ __forceinline__ bf16* Wgu_t() const { return (bf16*)((unsigned char*)out + OUT_WGU); }
; __device__ __forceinline__ P0Item p0_decode(Frame& F, int it, int n4) {
;     ...
;     if (r < I_IN) { const int nblk = NP1 / 64, kb = r / nblk, nb = r % nblk, n = nb * 64 + n4;
;         const int sc = n < SRC_GLR ? n : n + GRANK;
;         q.srcp = F.w_in + sc; q.ldw = DIN; q.kscale = F.norm1_w; q.K = D; q.WT = F.Win_t(); q.n0 = nb * 64; q.k0 = kb * 64; return q; }
;     r -= I_IN;
;     if (r < I_OUT) { const int nblk = D / 64, kb = r / nblk, nb = r % nblk;
;         q.srcp = F.w_out + nb * 64 + n4; q.ldw = D; q.kscale = nullptr; q.K = D; q.WT = F.Wout_t(); q.n0 = nb * 64; q.k0 = kb * 64; return q; }
;     r -= I_OUT;
;     if (r < I_GU) { const int nblk = 2 * FF / 64, kb = r / nblk, nb = r % nblk, n0 = nb * 64, pn = n0 >> 8, wc = (n0 >> 6) & 3, bj = n4 >> 5, hl = 32 * wc + (n4 & 31);
;         q.srcp = (bj ? F.w_up : F.w_gate) + pn * 128 + hl; q.ldw = FF; q.kscale = F.norm2_w; q.K = D; q.WT = F.Wgu_t(); q.n0 = n0; q.k0 = kb * 64; return q; }
;     r -= I_GU;
;     { const int nblk = D / 64, kb = r / nblk, nb = r % nblk;
;         q.srcp = F.w_down + nb * 64 + n4; q.ldw = D; q.kscale = nullptr; q.K = FF; q.WT = F.Wdown_t(); q.n0 = nb * 64; q.k0 = kb * 64; return q; }
; __global__ void __launch_bounds__(NTHREADS, 2) hybrid_fwd(Args args) {
;     ...
;                 p1_glr(F, sw, nshort * NWAVES); p0_items<true>(F, P0_NITEMS - P0_DEFER_ITEMS, P0_NITEMS, sw, nshort * NWAVES); }
;             else if ((NT % F.G) == 0) { p1_glr(F, F.vcu * NWAVES + F.wave, F.G * NWAVES); p0_items<true>(F, P0_NITEMS - P0_DEFER_ITEMS, P0_NITEMS, F.vcu * NWAVES + F.wave, F.G * NWAVES); }
.LBB0_228:
	v_lshlrev_b32_e32 v20, 2, v183
	s_add_i32 s67, s0, 0x2f28
	v_and_b32_e32 v142, 60, v20
	s_cmpk_gt_i32 s0, 0x11f7
	v_lshrrev_b32_e32 v143, 4, v183
	s_cbranch_scc1 .LBB0_233
	s_cmpk_gt_i32 s0, 0xecf7
	s_cbranch_scc0 .LBB0_234
	s_cmpk_gt_u32 s67, 0x1cff
	s_cbranch_scc0 .LBB0_235
	s_cmpk_gt_u32 s67, 0x32ff
	s_cbranch_scc0 .LBB0_236
	s_lshl_b32 s0, s67, 6
	s_and_b32 s64, s0, 0x7c0
	s_lshl_b32 s0, s64, 2
	s_add_u32 s0, s94, s0
	s_addc_u32 s1, s95, 0
	v_lshlrev_b32_e32 v2, 2, v142
	v_mov_b32_e32 v3, 0
	s_add_u32 s18, s56, 0x1200000
	v_lshl_add_u64 v[18:19], s[0:1], 0, v[2:3]
	s_addc_u32 s19, s57, 0
	s_lshl_b32 s0, s67, 1
	s_and_b32 s0, s0, 0x7fffffc0
	s_add_i32 s65, s0, 0xffff9a00
	s_mov_b64 s[20:21], 0
	s_mov_b64 s[6:7], 0
	s_branch .LBB0_237

;     __device__ __forceinline__ bf16* Win_t() const { return (bf16*)(ws + WS_WIN); }
;     __device__ __forceinline__ bf16* Wout_t() const { return (bf16*)(ws + WS_WOUT); }
;     __device__ __forceinline__ bf16* Wdown_t() const { return (bf16*)(ws + WS_WDOWN); }
;     __device__ __forceinline__ bf16* Wgu_t() const { return (bf16*)((unsigned char*)out + OUT_WGU); }
; __device__ __forceinline__ P0Item p0_decode(Frame& F, int it, int n4) {
;     ...
;     if (r < I_IN) { const int nblk = NP1 / 64, kb = r / nblk, nb = r % nblk, n = nb * 64 + n4;
;         const int sc = n < SRC_GLR ? n : n + GRANK;
;         q.srcp = F.w_in + sc; q.ldw = DIN; q.kscale = F.norm1_w; q.K = D; q.WT = F.Win_t(); q.n0 = nb * 64; q.k0 = kb * 64; return q; }
;     r -= I_IN;
;     if (r < I_OUT) { const int nblk = D / 64, kb = r / nblk, nb = r % nblk;
;         q.srcp = F.w_out + nb * 64 + n4; q.ldw = D; q.kscale = nullptr; q.K = D; q.WT = F.Wout_t(); q.n0 = nb * 64; q.k0 = kb * 64; return q; }
;     r -= I_OUT;
;     if (r < I_GU) { const int nblk = 2 * FF / 64, kb = r / nblk, nb = r % nblk, n0 = nb * 64, pn = n0 >> 8, wc = (n0 >> 6) & 3, bj = n4 >> 5, hl = 32 * wc + (n4 & 31);
;         q.srcp = (bj ? F.w_up : F.w_gate) + pn * 128 + hl; q.ldw = FF; q.kscale = F.norm2_w; q.K = D; q.WT = F.Wgu_t(); q.n0 = n0; q.k0 = kb * 64; return q; }
;     r -= I_GU;
;     { const int nblk = D / 64, kb = r / nblk, nb = r % nblk;
;         q.srcp = F.w_down + nb * 64 + n4; q.ldw = D; q.kscale = nullptr; q.K = FF; q.WT = F.Wdown_t(); q.n0 = nb * 64; q.k0 = kb * 64; return q; }
; __global__ void __launch_bounds__(NTHREADS, 2) hybrid_fwd(Args args) {
;     ...
;                 p1_glr(F, sw, nshort * NWAVES); p0_items<true>(F, P0_NITEMS - P0_DEFER_ITEMS, P0_NITEMS, sw, nshort * NWAVES); }
;             else if ((NT % F.G) == 0) { p1_glr(F, F.vcu * NWAVES + F.wave, F.G * NWAVES); p0_items<true>(F, P0_NITEMS - P0_DEFER_ITEMS, P0_NITEMS, F.vcu * NWAVES + F.wave, F.G * NWAVES); }
.LBB0_399:
	v_lshlrev_b32_e32 v20, 2, v183
	s_add_i32 s35, s0, 0x2f28
	v_and_b32_e32 v142, 60, v20
	s_cmpk_gt_i32 s0, 0x11f7
	v_lshrrev_b32_e32 v143, 4, v183
	s_cbranch_scc1 .LBB0_421
	s_cmpk_gt_i32 s0, 0xecf7
	s_cbranch_scc0 .LBB0_439
	s_cmpk_gt_u32 s35, 0x1cff
	s_cbranch_scc0 .LBB0_912
	s_cmpk_gt_u32 s35, 0x32ff
	s_cbranch_scc0 .LBB0_913
	s_lshl_b32 s0, s35, 6
	s_and_b32 s36, s0, 0x7c0
	s_lshl_b32 s0, s36, 2
	s_add_u32 s0, s94, s0
	s_addc_u32 s1, s95, 0
	s_waitcnt vmcnt(0)
	v_lshlrev_b32_e32 v2, 2, v142
	v_mov_b32_e32 v3, 0
	s_add_u32 s6, s56, 0x1200000
	v_lshl_add_u64 v[18:19], s[0:1], 0, v[2:3]
	s_addc_u32 s7, s57, 0
	s_lshl_b32 s0, s35, 1
	s_and_b32 s0, s0, 0x7fffffc0
	s_add_i32 s37, s0, 0xffff9a00
	s_mov_b64 s[18:19], 0
	s_mov_b64 s[4:5], 0
	s_branch .LBB0_914
